# prologue/epilogue de-serialisation: attention mode-0 unit epilogue issues all eight subw loads up-front (v[98:121]) instead of three load-wait-store round trips
# speedup vs baseline: 1.0055x; 1.0055x over previous
.LBB0_679:
	s_cmpk_gt_u32 s18, 0xff
	s_waitcnt lgkmcnt(0)
	s_barrier
	s_cbranch_scc1 .LBB0_634
	ds_read2st64_b32 v[30:31], v1 offset1:1
	ds_read2st64_b32 v[32:33], v1 offset0:2 offset1:3
	ds_read2st64_b32 v[44:45], v1 offset0:4 offset1:5
	ds_read2st64_b32 v[46:47], v1 offset0:6 offset1:7
	ds_read2st64_b32 v[48:49], v1 offset0:8 offset1:9
	ds_read2st64_b32 v[50:51], v1 offset0:10 offset1:11
	ds_read2st64_b32 v[52:53], v1 offset0:12 offset1:13
	ds_read2st64_b32 v[26:27], v1 offset0:14 offset1:15
	ds_read2st64_b32 v[54:55], v1 offset0:24 offset1:25
	ds_read2st64_b32 v[56:57], v1 offset0:26 offset1:27
	ds_read2st64_b32 v[58:59], v1 offset0:28 offset1:29
	ds_read2st64_b32 v[28:29], v1 offset0:30 offset1:31
	ds_read2st64_b32 v[60:61], v1 offset0:16 offset1:17
	ds_read2st64_b32 v[62:63], v1 offset0:18 offset1:19
	ds_read2st64_b32 v[64:65], v1 offset0:20 offset1:21
	ds_read2st64_b32 v[66:67], v1 offset0:22 offset1:23
	s_waitcnt lgkmcnt(4)
	v_pk_fma_f32 v[70:71], v[192:193], v[28:29], v[16:17] neg_lo:[1,0,0] neg_hi:[1,0,0]
	v_pk_fma_f32 v[68:69], v[192:193], v[26:27], v[14:15] neg_lo:[1,0,0] neg_hi:[1,0,0]
	v_pk_mul_f32 v[14:15], v[70:71], v[70:71]
	s_waitcnt lgkmcnt(3)
	v_pk_fma_f32 v[40:41], v[192:193], v[60:61], v[40:41] neg_lo:[1,0,0] neg_hi:[1,0,0]
	v_pk_fma_f32 v[72:73], v[68:69], v[68:69], v[14:15]
	global_load_dwordx4 v[14:17], v162, s[84:85]
	global_load_dwordx4 v[26:29], v162, s[84:85] offset:128
	global_load_dwordx4 v[98:101], v162, s[84:85] offset:32
	global_load_dwordx4 v[102:105], v162, s[84:85] offset:160
	global_load_dwordx4 v[106:109], v162, s[84:85] offset:64
	global_load_dwordx4 v[110:113], v162, s[84:85] offset:192
	global_load_dwordx4 v[114:117], v162, s[84:85] offset:96
	global_load_dwordx4 v[118:121], v162, s[84:85] offset:224
	s_waitcnt lgkmcnt(2)
	v_pk_fma_f32 v[42:43], v[192:193], v[62:63], v[42:43] neg_lo:[1,0,0] neg_hi:[1,0,0]
	v_pk_mul_f32 v[60:61], v[40:41], v[40:41]
	v_pk_fma_f32 v[30:31], v[192:193], v[30:31], v[36:37] neg_lo:[1,0,0] neg_hi:[1,0,0]
	v_pk_mul_f32 v[62:63], v[42:43], v[42:43]
	v_pk_fma_f32 v[32:33], v[192:193], v[32:33], v[38:39] neg_lo:[1,0,0] neg_hi:[1,0,0]
	v_pk_fma_f32 v[36:37], v[30:31], v[30:31], v[60:61]
	v_pk_fma_f32 v[38:39], v[32:33], v[32:33], v[62:63]
	v_pk_add_f32 v[36:37], v[36:37], v[36:37] op_sel:[0,1] op_sel_hi:[1,0]
	s_waitcnt lgkmcnt(1)
	v_pk_fma_f32 v[22:23], v[192:193], v[64:65], v[22:23] neg_lo:[1,0,0] neg_hi:[1,0,0]
	v_pk_add_f32 v[36:37], v[36:37], v[38:39]
	v_pk_mul_f32 v[60:61], v[22:23], v[22:23]
	v_pk_fma_f32 v[18:19], v[192:193], v[44:45], v[18:19] neg_lo:[1,0,0] neg_hi:[1,0,0]
	v_pk_add_f32 v[36:37], v[36:37], v[38:39] op_sel:[0,1] op_sel_hi:[1,0]
	s_waitcnt lgkmcnt(0)
	v_pk_fma_f32 v[24:25], v[192:193], v[66:67], v[24:25] neg_lo:[1,0,0] neg_hi:[1,0,0]
	v_pk_fma_f32 v[44:45], v[18:19], v[18:19], v[60:61]
	v_pk_mul_f32 v[38:39], v[24:25], v[24:25]
	v_pk_fma_f32 v[20:21], v[192:193], v[46:47], v[20:21] neg_lo:[1,0,0] neg_hi:[1,0,0]
	v_pk_add_f32 v[36:37], v[36:37], v[44:45]
	v_pk_fma_f32 v[38:39], v[20:21], v[20:21], v[38:39]
	v_pk_add_f32 v[36:37], v[36:37], v[44:45] op_sel:[0,1] op_sel_hi:[1,0]
	v_pk_fma_f32 v[12:13], v[192:193], v[56:57], v[12:13] neg_lo:[1,0,0] neg_hi:[1,0,0]
	v_pk_add_f32 v[36:37], v[36:37], v[38:39]
	v_pk_fma_f32 v[10:11], v[192:193], v[54:55], v[10:11] neg_lo:[1,0,0] neg_hi:[1,0,0]
	v_pk_add_f32 v[36:37], v[36:37], v[38:39] op_sel:[0,1] op_sel_hi:[1,0]
	v_pk_mul_f32 v[38:39], v[12:13], v[12:13]
	v_pk_fma_f32 v[46:47], v[192:193], v[50:51], v[8:9] neg_lo:[1,0,0] neg_hi:[1,0,0]
	v_pk_mul_f32 v[44:45], v[10:11], v[10:11]
	v_pk_fma_f32 v[8:9], v[46:47], v[46:47], v[38:39]
	v_pk_fma_f32 v[38:39], v[192:193], v[48:49], v[2:3] neg_lo:[1,0,0] neg_hi:[1,0,0]
	v_lshlrev_b64 v[34:35], 11, v[34:35]
	v_pk_fma_f32 v[2:3], v[38:39], v[38:39], v[44:45]
	v_pk_fma_f32 v[44:45], v[192:193], v[52:53], v[4:5] neg_lo:[1,0,0] neg_hi:[1,0,0]
	v_pk_add_f32 v[36:37], v[36:37], v[2:3]
	s_lshl_b32 s92, s74, 7
	v_pk_add_f32 v[2:3], v[36:37], v[2:3] op_sel:[0,1] op_sel_hi:[1,0]
	v_pk_fma_f32 v[36:37], v[192:193], v[58:59], v[6:7] neg_lo:[1,0,0] neg_hi:[1,0,0]
	v_pk_add_f32 v[2:3], v[2:3], v[8:9]
	v_pk_mul_f32 v[6:7], v[36:37], v[36:37]
	v_pk_add_f32 v[2:3], v[2:3], v[8:9] op_sel:[0,1] op_sel_hi:[1,0]
	v_pk_fma_f32 v[4:5], v[44:45], v[44:45], v[6:7]
	s_nop 0
	v_pk_add_f32 v[2:3], v[2:3], v[4:5]
	s_nop 0
	v_pk_add_f32 v[2:3], v[2:3], v[4:5] op_sel:[0,1] op_sel_hi:[1,0]
	s_nop 0
	v_pk_add_f32 v[2:3], v[2:3], v[72:73]
	s_nop 0
	v_pk_add_f32 v[2:3], v[2:3], v[72:73] op_sel:[0,1] op_sel_hi:[1,0]
	s_nop 0
	v_mov_b32_e32 v1, v2
	s_nop 1
	v_permlane32_swap_b32_e32 v2, v1
	v_add_f32_e32 v1, v2, v1
	v_fmamk_f32 v1, v1, 0x3c800000, v228
	v_mul_f32_e32 v2, 0x4f800000, v1
	v_cmp_gt_f32_e32 vcc, s49, v1
	s_nop 1
	v_cndmask_b32_e32 v1, v1, v2, vcc
	v_sqrt_f32_e32 v4, v1
	v_lshl_add_u64 v[2:3], s[8:9], 0, v[34:35]
	v_lshl_add_u64 v[2:3], v[2:3], 0, s[92:93]
	v_add_u32_e32 v5, -1, v4
	v_fma_f32 v6, -v5, v4, v1
	v_cmp_ge_f32_e64 s[0:1], 0, v6
	v_add_u32_e32 v6, 1, v4
	s_nop 0
	v_cndmask_b32_e64 v5, v4, v5, s[0:1]
	v_fma_f32 v4, -v6, v4, v1
	v_cmp_lt_f32_e64 s[0:1], 0, v4
	s_nop 1
	v_cndmask_b32_e64 v4, v5, v6, s[0:1]
	v_mul_f32_e32 v5, 0x37800000, v4
	v_cndmask_b32_e32 v4, v4, v5, vcc
	v_cmp_class_f32_e32 vcc, v1, v229
	v_mov_b32_e32 v5, v0
	s_nop 0
	v_cndmask_b32_e32 v1, v4, v1, vcc
	v_div_scale_f32 v6, s[0:1], v1, v1, v234
	v_rcp_f32_e32 v7, v6
	v_lshlrev_b32_e32 v4, 3, v180
	v_lshl_add_u64 v[34:35], v[2:3], 0, v[4:5]
	v_fma_f32 v2, -v6, v7, 1.0
	v_fmac_f32_e32 v7, v2, v7
	v_div_scale_f32 v2, vcc, v234, v1, v234
	v_mul_f32_e32 v3, v2, v7
	v_fma_f32 v4, -v6, v3, v2
	v_fmac_f32_e32 v3, v4, v7
	v_fma_f32 v2, -v6, v3, v2
	v_div_fmas_f32 v2, v2, v7, v3
	v_div_fixup_f32 v48, v2, v1, v234
	v_pk_mul_f32 v[2:3], v[30:31], v[48:49] op_sel_hi:[1,0]
	v_pk_mul_f32 v[4:5], v[32:33], v[48:49] op_sel_hi:[1,0]
	s_waitcnt vmcnt(0)
	v_pk_mul_f32 v[2:3], v[14:15], v[2:3]
	v_pk_mul_f32 v[4:5], v[16:17], v[4:5]
	v_cvt_pk_bf16_f32 v2, v2, v3
	v_cvt_pk_bf16_f32 v3, v4, v5
	v_pk_mul_f32 v[4:5], v[40:41], v[48:49] op_sel_hi:[1,0]
	v_pk_mul_f32 v[6:7], v[42:43], v[48:49] op_sel_hi:[1,0]
	s_waitcnt vmcnt(0)
	v_pk_mul_f32 v[4:5], v[26:27], v[4:5]
	v_pk_mul_f32 v[6:7], v[28:29], v[6:7]
	v_cvt_pk_bf16_f32 v4, v4, v5
	v_cvt_pk_bf16_f32 v5, v6, v7
	global_store_dwordx2 v[34:35], v[2:3], off
	global_store_dwordx2 v[34:35], v[4:5], off offset:64
	v_pk_mul_f32 v[14:15], v[18:19], v[48:49] op_sel_hi:[1,0]
	v_pk_mul_f32 v[16:17], v[20:21], v[48:49] op_sel_hi:[1,0]
	v_pk_mul_f32 v[18:19], v[22:23], v[48:49] op_sel_hi:[1,0]
	v_pk_mul_f32 v[20:21], v[24:25], v[48:49] op_sel_hi:[1,0]
	v_pk_mul_f32 v[10:11], v[10:11], v[48:49] op_sel_hi:[1,0]
	v_pk_mul_f32 v[12:13], v[12:13], v[48:49] op_sel_hi:[1,0]
	v_pk_mul_f32 v[2:3], v[98:99], v[14:15]
	v_pk_mul_f32 v[4:5], v[100:101], v[16:17]
	v_pk_mul_f32 v[6:7], v[102:103], v[18:19]
	v_pk_mul_f32 v[8:9], v[104:105], v[20:21]
	v_cvt_pk_bf16_f32 v2, v2, v3
	v_cvt_pk_bf16_f32 v3, v4, v5
	v_cvt_pk_bf16_f32 v4, v6, v7
	v_cvt_pk_bf16_f32 v5, v8, v9
	global_store_dwordx2 v[34:35], v[2:3], off offset:16
	global_store_dwordx2 v[34:35], v[4:5], off offset:80
	v_pk_mul_f32 v[14:15], v[38:39], v[48:49] op_sel_hi:[1,0]
	v_pk_mul_f32 v[16:17], v[46:47], v[48:49] op_sel_hi:[1,0]
	v_pk_mul_f32 v[2:3], v[14:15], v[106:107]
	v_pk_mul_f32 v[4:5], v[16:17], v[108:109]
	v_pk_mul_f32 v[6:7], v[10:11], v[110:111]
	v_pk_mul_f32 v[8:9], v[12:13], v[112:113]
	v_cvt_pk_bf16_f32 v2, v2, v3
	v_cvt_pk_bf16_f32 v3, v4, v5
	v_cvt_pk_bf16_f32 v4, v6, v7
	v_cvt_pk_bf16_f32 v5, v8, v9
	global_store_dwordx2 v[34:35], v[2:3], off offset:32
	global_store_dwordx2 v[34:35], v[4:5], off offset:96
	v_pk_mul_f32 v[10:11], v[44:45], v[48:49] op_sel_hi:[1,0]
	v_pk_mul_f32 v[12:13], v[68:69], v[48:49] op_sel_hi:[1,0]
	v_pk_mul_f32 v[14:15], v[36:37], v[48:49] op_sel_hi:[1,0]
	v_pk_mul_f32 v[16:17], v[70:71], v[48:49] op_sel_hi:[1,0]
	v_pk_mul_f32 v[2:3], v[10:11], v[114:115]
	v_pk_mul_f32 v[4:5], v[12:13], v[116:117]
	v_pk_mul_f32 v[6:7], v[14:15], v[118:119]
	v_pk_mul_f32 v[8:9], v[16:17], v[120:121]
	v_cvt_pk_bf16_f32 v2, v2, v3
	v_cvt_pk_bf16_f32 v3, v4, v5
	v_cvt_pk_bf16_f32 v4, v6, v7
	v_cvt_pk_bf16_f32 v5, v8, v9
	global_store_dwordx2 v[34:35], v[2:3], off offset:48
	global_store_dwordx2 v[34:35], v[4:5], off offset:112
	s_branch .LBB0_634
